# v9 with the tile t+2 LDS-DMA issued inside the PV(x10) group instead of the S0 group
# speedup vs baseline: 1.0048x; 1.0024x over previous
.LBB0_531:
	s_add_i32 s10, s33, 2
	s_cmp_ge_u32 s10, s28
	s_cselect_b64 s[22:23], -1, 0
	s_mov_b64 s[34:35], -1
	s_cmp_gt_i32 s33, s21
	s_cbranch_scc1 .Lat1_skip
	s_and_b64 vcc, exec, s[22:23]
	s_cbranch_vccnz .Lat1_nodma
	s_setprio 3
	v_mov_b32_e32 v206, v217
	s_mul_i32 s10, s0, 0xa000
	v_lshlrev_b32_e32 v209, 3, v206
	v_lshrrev_b32_e32 v207, 1, v206
	v_lshlrev_b32_e32 v208, 7, v206
	v_and_b32_e32 v209, 8, v209
	v_ashrrev_i32_e32 v206, 5, v206
	v_add_u32_e32 v206, v209, v206
	v_and_b32_e32 v208, 0xf00, v208
	v_bitop3_b32 v209, v206, v207, 7 bitop3:0x78
	v_add_u32_e32 v210, 2, v206
	v_add_u32_e32 v211, 4, v206
	v_add_u32_e32 v206, 6, v206
	v_add_u32_e32 v208, s10, v208
	v_bitop3_b32 v210, v210, v207, 7 bitop3:0x78
	v_bitop3_b32 v211, v211, v207, 7 bitop3:0x78
	v_bitop3_b32 v206, v206, v207, 7 bitop3:0x78
	v_lshl_add_u32 v14, v209, 4, v208
	v_lshl_add_u32 v15, v210, 4, v208
	v_lshl_add_u32 v176, v211, 4, v208
	v_lshl_add_u32 v177, v206, 4, v208
	ds_read_b128 v[144:147], v14 offset:0
	ds_read_b128 v[148:151], v15 offset:0
	ds_read_b128 v[152:155], v176 offset:0
	ds_read_b128 v[156:159], v177 offset:0
	ds_read_b128 v[160:163], v14 offset:8192
	ds_read_b128 v[164:167], v15 offset:8192
	ds_read_b128 v[168:171], v176 offset:8192
	ds_read_b128 v[172:175], v177 offset:8192
	ds_read_b128 v[2:5], v14 offset:16384
	ds_read_b128 v[6:9], v15 offset:16384
	ds_read_b128 v[10:13], v176 offset:16384
	ds_read_b128 v[238:241], v177 offset:16384
	s_waitcnt lgkmcnt(8)
	v_mfma_f32_32x32x16_bf16 v[80:95], v[144:147], v[132:135], 0
	v_mfma_f32_32x32x16_bf16 v[80:95], v[148:151], v[128:131], v[80:95]
	v_mfma_f32_32x32x16_bf16 v[80:95], v[152:155], v[124:127], v[80:95]
	v_mfma_f32_32x32x16_bf16 v[80:95], v[156:159], v[120:123], v[80:95]
	ds_read_b128 v[144:147], v14 offset:4096
	ds_read_b128 v[148:151], v15 offset:4096
	ds_read_b128 v[152:155], v176 offset:4096
	ds_read_b128 v[156:159], v177 offset:4096
	s_waitcnt lgkmcnt(8)
	v_mfma_f32_32x32x16_bf16 v[80:95], v[160:163], v[116:119], v[80:95]
	v_mfma_f32_32x32x16_bf16 v[80:95], v[164:167], v[112:115], v[80:95]
	v_mfma_f32_32x32x16_bf16 v[80:95], v[168:171], v[108:111], v[80:95]
	v_mfma_f32_32x32x16_bf16 v[80:95], v[172:175], v[104:107], v[80:95]
	ds_read_b128 v[160:163], v14 offset:12288
	ds_read_b128 v[164:167], v15 offset:12288
	ds_read_b128 v[168:171], v176 offset:12288
	ds_read_b128 v[172:175], v177 offset:12288
	s_waitcnt lgkmcnt(8)
	v_mfma_f32_32x32x16_bf16 v[80:95], v[2:5], v[100:103], v[80:95]
	v_mfma_f32_32x32x16_bf16 v[80:95], v[6:9], v[140:143], v[80:95]
	v_mfma_f32_32x32x16_bf16 v[80:95], v[10:13], v[96:99], v[80:95]
	v_mfma_f32_32x32x16_bf16 v[80:95], v[238:241], v[136:139], v[80:95]
	s_setprio 2
	ds_read_b128 v[2:5], v14 offset:20480
	ds_read_b128 v[6:9], v15 offset:20480
	ds_read_b128 v[10:13], v176 offset:20480
	ds_read_b128 v[238:241], v177 offset:20480
	s_waitcnt lgkmcnt(8)
	v_mfma_f32_32x32x16_bf16 v[184:199], v[144:147], v[132:135], 0
	v_mfma_f32_32x32x16_bf16 v[184:199], v[148:151], v[128:131], v[184:199]
	v_mfma_f32_32x32x16_bf16 v[184:199], v[152:155], v[124:127], v[184:199]
	v_mfma_f32_32x32x16_bf16 v[184:199], v[156:159], v[120:123], v[184:199]
	ds_read_b128 v[144:147], v14 offset:24576
	ds_read_b128 v[148:151], v14 offset:28672
	ds_read_b128 v[152:155], v14 offset:32768
	ds_read_b128 v[156:159], v14 offset:36864
	s_waitcnt lgkmcnt(8)
	v_mfma_f32_32x32x16_bf16 v[184:199], v[160:163], v[116:119], v[184:199]
	v_med3_f32 v80, v80, s4, v236
	v_exp_f32_e32 v80, v80
	v_med3_f32 v81, v81, s4, v236
	v_exp_f32_e32 v81, v81
	v_mfma_f32_32x32x16_bf16 v[184:199], v[164:167], v[112:115], v[184:199]
	v_med3_f32 v82, v82, s4, v236
	v_exp_f32_e32 v82, v82
	v_med3_f32 v83, v83, s4, v236
	v_exp_f32_e32 v83, v83
	v_mfma_f32_32x32x16_bf16 v[184:199], v[168:171], v[108:111], v[184:199]
	v_med3_f32 v84, v84, s4, v236
	v_exp_f32_e32 v84, v84
	v_med3_f32 v85, v85, s4, v236
	v_exp_f32_e32 v85, v85
	v_mfma_f32_32x32x16_bf16 v[184:199], v[172:175], v[104:107], v[184:199]
	v_med3_f32 v86, v86, s4, v236
	v_exp_f32_e32 v86, v86
	v_med3_f32 v87, v87, s4, v236
	v_exp_f32_e32 v87, v87
	ds_read_b128 v[160:163], v15 offset:24576
	ds_read_b128 v[164:167], v15 offset:28672
	ds_read_b128 v[168:171], v15 offset:32768
	ds_read_b128 v[172:175], v15 offset:36864
	s_waitcnt lgkmcnt(8)
	v_mfma_f32_32x32x16_bf16 v[184:199], v[2:5], v[100:103], v[184:199]
	v_med3_f32 v88, v88, s4, v236
	v_exp_f32_e32 v88, v88
	v_med3_f32 v89, v89, s4, v236
	v_exp_f32_e32 v89, v89
	v_add_f32_e32 v200, v80, v81
	v_add_f32_e32 v200, v200, v82
	v_mfma_f32_32x32x16_bf16 v[184:199], v[6:9], v[140:143], v[184:199]
	v_med3_f32 v90, v90, s4, v236
	v_exp_f32_e32 v90, v90
	v_med3_f32 v91, v91, s4, v236
	v_exp_f32_e32 v91, v91
	v_add_f32_e32 v200, v200, v83
	v_add_f32_e32 v200, v200, v84
	v_mfma_f32_32x32x16_bf16 v[184:199], v[10:13], v[96:99], v[184:199]
	v_med3_f32 v92, v92, s4, v236
	v_exp_f32_e32 v92, v92
	v_med3_f32 v93, v93, s4, v236
	v_exp_f32_e32 v93, v93
	v_add_f32_e32 v200, v200, v85
	v_add_f32_e32 v200, v200, v86
	v_mfma_f32_32x32x16_bf16 v[184:199], v[238:241], v[136:139], v[184:199]
	v_med3_f32 v94, v94, s4, v236
	v_exp_f32_e32 v94, v94
	v_med3_f32 v95, v95, s4, v236
	v_exp_f32_e32 v95, v95
	v_add_f32_e32 v200, v200, v87
	s_setprio 1
	ds_read_b128 v[2:5], v176 offset:24576
	ds_read_b128 v[6:9], v176 offset:28672
	ds_read_b128 v[10:13], v176 offset:32768
	ds_read_b128 v[238:241], v176 offset:36864
	v_cvt_pk_bf16_f32 v80, v80, v81
	v_cvt_pk_bf16_f32 v81, v82, v83
	v_cvt_pk_bf16_f32 v82, v84, v85
	v_cvt_pk_bf16_f32 v83, v86, v87
	v_add_f32_e32 v200, v200, v88
	v_add_f32_e32 v200, v200, v89
	s_waitcnt lgkmcnt(8)
	v_mfma_f32_32x32x16_bf16 v[64:79], v[80:83], v[144:147], v[64:79]
	v_med3_f32 v184, v184, s4, v236
	v_exp_f32_e32 v184, v184
	v_med3_f32 v185, v185, s4, v236
	v_exp_f32_e32 v185, v185
	v_add_f32_e32 v200, v200, v90
	v_add_f32_e32 v200, v200, v91
	v_mfma_f32_32x32x16_bf16 v[48:63], v[80:83], v[148:151], v[48:63]
	v_med3_f32 v186, v186, s4, v236
	v_exp_f32_e32 v186, v186
	v_med3_f32 v187, v187, s4, v236
	v_exp_f32_e32 v187, v187
	v_add_f32_e32 v200, v200, v92
	v_add_f32_e32 v200, v200, v93
	v_mfma_f32_32x32x16_bf16 v[32:47], v[80:83], v[152:155], v[32:47]
	v_med3_f32 v188, v188, s4, v236
	v_exp_f32_e32 v188, v188
	v_med3_f32 v189, v189, s4, v236
	v_exp_f32_e32 v189, v189
	v_add_f32_e32 v200, v200, v94
	v_add_f32_e32 v200, v200, v95
	v_mfma_f32_32x32x16_bf16 v[16:31], v[80:83], v[156:159], v[16:31]
	v_med3_f32 v190, v190, s4, v236
	v_exp_f32_e32 v190, v190
	v_med3_f32 v191, v191, s4, v236
	v_exp_f32_e32 v191, v191
	v_cvt_pk_bf16_f32 v84, v88, v89
	v_cvt_pk_bf16_f32 v85, v90, v91
	v_cvt_pk_bf16_f32 v86, v92, v93
	v_cvt_pk_bf16_f32 v87, v94, v95
	ds_read_b128 v[144:147], v177 offset:24576
	ds_read_b128 v[148:151], v177 offset:28672
	ds_read_b128 v[152:155], v177 offset:32768
	ds_read_b128 v[156:159], v177 offset:36864
	s_waitcnt lgkmcnt(8)
	v_mfma_f32_32x32x16_bf16 v[64:79], v[84:87], v[160:163], v[64:79]
	v_med3_f32 v192, v192, s4, v236
	v_exp_f32_e32 v192, v192
	v_med3_f32 v193, v193, s4, v236
	v_exp_f32_e32 v193, v193
	v_add_f32_e32 v201, v184, v185
	v_add_f32_e32 v201, v201, v186
	v_mfma_f32_32x32x16_bf16 v[48:63], v[84:87], v[164:167], v[48:63]
	v_med3_f32 v194, v194, s4, v236
	v_exp_f32_e32 v194, v194
	v_med3_f32 v195, v195, s4, v236
	v_exp_f32_e32 v195, v195
	v_add_f32_e32 v201, v201, v187
	v_add_f32_e32 v201, v201, v188
	v_mfma_f32_32x32x16_bf16 v[32:47], v[84:87], v[168:171], v[32:47]
	v_med3_f32 v196, v196, s4, v236
	v_exp_f32_e32 v196, v196
	v_med3_f32 v197, v197, s4, v236
	v_exp_f32_e32 v197, v197
	v_add_f32_e32 v201, v201, v189
	v_mfma_f32_32x32x16_bf16 v[16:31], v[84:87], v[172:175], v[16:31]
	v_med3_f32 v198, v198, s4, v236
	v_exp_f32_e32 v198, v198
	v_med3_f32 v199, v199, s4, v236
	v_exp_f32_e32 v199, v199
	v_add_f32_e32 v201, v201, v190
	v_cvt_pk_bf16_f32 v184, v184, v185
	v_cvt_pk_bf16_f32 v185, v186, v187
	v_cvt_pk_bf16_f32 v186, v188, v189
	v_cvt_pk_bf16_f32 v187, v190, v191
	v_add_f32_e32 v201, v201, v191
	s_setprio 0
	s_waitcnt lgkmcnt(4)
	v_mfma_f32_32x32x16_bf16 v[64:79], v[184:187], v[2:5], v[64:79]
	v_mad_u64_u32 v[202:203], s[10:11], s86, v228, v[180:181]
	s_mul_i32 s10, s7, 0xa000
	s_add_i32 s10, s9, s10
	s_mov_b32 m0, s10
	v_lshl_add_u64 v[204:205], v[202:203], 0, s[94:95]
	global_load_lds_dwordx4 v[202:203], off
	v_add_f32_e32 v201, v201, v192
	v_add_f32_e32 v201, v201, v193
	v_add_f32_e32 v201, v201, v194
	v_mfma_f32_32x32x16_bf16 v[48:63], v[184:187], v[6:9], v[48:63]
	s_add_i32 m0, s10, 0x2000
	v_lshl_add_u64 v[202:203], v[202:203], 0, s[96:97]
	global_load_lds_dwordx4 v[204:205], off
	v_add_f32_e32 v201, v201, v195
	v_add_f32_e32 v201, v201, v196
	v_add_f32_e32 v201, v201, v197
	v_mfma_f32_32x32x16_bf16 v[32:47], v[184:187], v[10:13], v[32:47]
	s_add_i32 m0, s10, 0x4000
	s_nop 0
	global_load_lds_dwordx4 v[202:203], off
	v_lshl_add_u64 v[202:203], s[86:87], 1, v[182:183]
	s_add_i32 m0, s10, 0x6000
	v_add_f32_e32 v201, v201, v198
	v_add_f32_e32 v201, v201, v199
	v_cvt_pk_bf16_f32 v188, v192, v193
	v_cvt_pk_bf16_f32 v189, v194, v195
	v_cvt_pk_bf16_f32 v190, v196, v197
	v_cvt_pk_bf16_f32 v191, v198, v199
	v_mfma_f32_32x32x16_bf16 v[16:31], v[184:187], v[238:241], v[16:31]
	global_load_lds_dwordx4 v[202:203], off
	v_lshl_add_u64 v[202:203], v[202:203], 0, s[92:93]
	s_add_i32 m0, s10, 0x8000
	v_add_f32_e32 v200, v200, v201
	v_add_f32_e32 v218, v218, v200
	s_waitcnt lgkmcnt(0)
	v_mfma_f32_32x32x16_bf16 v[64:79], v[188:191], v[144:147], v[64:79]
	global_load_lds_dwordx4 v[202:203], off
	v_mfma_f32_32x32x16_bf16 v[48:63], v[188:191], v[148:151], v[48:63]
	v_mfma_f32_32x32x16_bf16 v[32:47], v[188:191], v[152:155], v[32:47]
	v_mfma_f32_32x32x16_bf16 v[16:31], v[188:191], v[156:159], v[16:31]
	s_waitcnt vmcnt(5) lgkmcnt(0)
	s_branch .LBB0_530

.LBB0_574:
	s_add_i32 s10, s33, 2
	s_cmp_ge_i32 s10, s21
	s_cselect_b64 s[22:23], -1, 0
	s_mov_b64 s[34:35], -1
	s_cmp_gt_i32 s33, s9
	s_cbranch_scc1 .Lat2_skip
	s_and_b64 vcc, exec, s[22:23]
	s_cbranch_vccnz .Lat2_nodma
	s_setprio 3
	v_mov_b32_e32 v208, v222
	s_mul_i32 s10, s28, 0xa000
	v_lshlrev_b32_e32 v211, 3, v208
	v_lshrrev_b32_e32 v209, 1, v208
	v_lshlrev_b32_e32 v210, 7, v208
	v_and_b32_e32 v211, 8, v211
	v_ashrrev_i32_e32 v208, 5, v208
	v_add_u32_e32 v208, v211, v208
	v_and_b32_e32 v210, 0xf00, v210
	v_bitop3_b32 v211, v208, v209, 7 bitop3:0x78
	v_add_u32_e32 v212, 2, v208
	v_add_u32_e32 v213, 4, v208
	v_add_u32_e32 v208, 6, v208
	v_add_u32_e32 v210, s10, v210
	v_bitop3_b32 v212, v212, v209, 7 bitop3:0x78
	v_bitop3_b32 v213, v213, v209, 7 bitop3:0x78
	v_bitop3_b32 v208, v208, v209, 7 bitop3:0x78
	v_lshl_add_u32 v198, v211, 4, v210
	v_lshl_add_u32 v199, v212, 4, v210
	v_lshl_add_u32 v200, v213, 4, v210
	v_lshl_add_u32 v201, v208, 4, v210
	ds_read_b128 v[130:133], v198 offset:0
	ds_read_b128 v[134:137], v199 offset:0
	ds_read_b128 v[138:141], v200 offset:0
	ds_read_b128 v[142:145], v201 offset:0
	ds_read_b128 v[146:149], v198 offset:8192
	ds_read_b128 v[150:153], v199 offset:8192
	ds_read_b128 v[154:157], v200 offset:8192
	ds_read_b128 v[158:161], v201 offset:8192
	ds_read_b128 v[162:165], v198 offset:16384
	ds_read_b128 v[166:169], v199 offset:16384
	ds_read_b128 v[170:173], v200 offset:16384
	ds_read_b128 v[176:179], v201 offset:16384
	s_waitcnt lgkmcnt(8)
	v_mfma_f32_32x32x16_bf16 v[66:81], v[130:133], v[118:121], 0
	v_mfma_f32_32x32x16_bf16 v[66:81], v[134:137], v[114:117], v[66:81]
	v_mfma_f32_32x32x16_bf16 v[66:81], v[138:141], v[110:113], v[66:81]
	v_mfma_f32_32x32x16_bf16 v[66:81], v[142:145], v[106:109], v[66:81]
	ds_read_b128 v[130:133], v198 offset:4096
	ds_read_b128 v[134:137], v199 offset:4096
	ds_read_b128 v[138:141], v200 offset:4096
	ds_read_b128 v[142:145], v201 offset:4096
	s_waitcnt lgkmcnt(8)
	v_mfma_f32_32x32x16_bf16 v[66:81], v[146:149], v[102:105], v[66:81]
	v_mfma_f32_32x32x16_bf16 v[66:81], v[150:153], v[98:101], v[66:81]
	v_mfma_f32_32x32x16_bf16 v[66:81], v[154:157], v[94:97], v[66:81]
	v_mfma_f32_32x32x16_bf16 v[66:81], v[158:161], v[90:93], v[66:81]
	ds_read_b128 v[146:149], v198 offset:12288
	ds_read_b128 v[150:153], v199 offset:12288
	ds_read_b128 v[154:157], v200 offset:12288
	ds_read_b128 v[158:161], v201 offset:12288
	s_waitcnt lgkmcnt(8)
	v_mfma_f32_32x32x16_bf16 v[66:81], v[162:165], v[86:89], v[66:81]
	v_mfma_f32_32x32x16_bf16 v[66:81], v[166:169], v[126:129], v[66:81]
	v_mfma_f32_32x32x16_bf16 v[66:81], v[170:173], v[82:85], v[66:81]
	v_mfma_f32_32x32x16_bf16 v[66:81], v[176:179], v[122:125], v[66:81]
	s_setprio 2
	ds_read_b128 v[162:165], v198 offset:20480
	ds_read_b128 v[166:169], v199 offset:20480
	ds_read_b128 v[170:173], v200 offset:20480
	ds_read_b128 v[176:179], v201 offset:20480
	s_waitcnt lgkmcnt(8)
	v_mfma_f32_32x32x16_bf16 v[182:197], v[130:133], v[118:121], 0
	v_mfma_f32_32x32x16_bf16 v[182:197], v[134:137], v[114:117], v[182:197]
	v_mfma_f32_32x32x16_bf16 v[182:197], v[138:141], v[110:113], v[182:197]
	v_mfma_f32_32x32x16_bf16 v[182:197], v[142:145], v[106:109], v[182:197]
	ds_read_b128 v[130:133], v198 offset:24576
	ds_read_b128 v[134:137], v198 offset:28672
	ds_read_b128 v[138:141], v198 offset:32768
	ds_read_b128 v[142:145], v198 offset:36864
	s_waitcnt lgkmcnt(8)
	v_mfma_f32_32x32x16_bf16 v[182:197], v[146:149], v[102:105], v[182:197]
	v_med3_f32 v66, v66, s4, v236
	v_exp_f32_e32 v66, v66
	v_med3_f32 v67, v67, s4, v236
	v_exp_f32_e32 v67, v67
	v_mfma_f32_32x32x16_bf16 v[182:197], v[150:153], v[98:101], v[182:197]
	v_med3_f32 v68, v68, s4, v236
	v_exp_f32_e32 v68, v68
	v_med3_f32 v69, v69, s4, v236
	v_exp_f32_e32 v69, v69
	v_mfma_f32_32x32x16_bf16 v[182:197], v[154:157], v[94:97], v[182:197]
	v_med3_f32 v70, v70, s4, v236
	v_exp_f32_e32 v70, v70
	v_med3_f32 v71, v71, s4, v236
	v_exp_f32_e32 v71, v71
	v_mfma_f32_32x32x16_bf16 v[182:197], v[158:161], v[90:93], v[182:197]
	v_med3_f32 v72, v72, s4, v236
	v_exp_f32_e32 v72, v72
	v_med3_f32 v73, v73, s4, v236
	v_exp_f32_e32 v73, v73
	ds_read_b128 v[146:149], v199 offset:24576
	ds_read_b128 v[150:153], v199 offset:28672
	ds_read_b128 v[154:157], v199 offset:32768
	ds_read_b128 v[158:161], v199 offset:36864
	s_waitcnt lgkmcnt(8)
	v_mfma_f32_32x32x16_bf16 v[182:197], v[162:165], v[86:89], v[182:197]
	v_med3_f32 v74, v74, s4, v236
	v_exp_f32_e32 v74, v74
	v_med3_f32 v75, v75, s4, v236
	v_exp_f32_e32 v75, v75
	v_add_f32_e32 v202, v66, v67
	v_add_f32_e32 v202, v202, v68
	v_mfma_f32_32x32x16_bf16 v[182:197], v[166:169], v[126:129], v[182:197]
	v_med3_f32 v76, v76, s4, v236
	v_exp_f32_e32 v76, v76
	v_med3_f32 v77, v77, s4, v236
	v_exp_f32_e32 v77, v77
	v_add_f32_e32 v202, v202, v69
	v_add_f32_e32 v202, v202, v70
	v_mfma_f32_32x32x16_bf16 v[182:197], v[170:173], v[82:85], v[182:197]
	v_med3_f32 v78, v78, s4, v236
	v_exp_f32_e32 v78, v78
	v_med3_f32 v79, v79, s4, v236
	v_exp_f32_e32 v79, v79
	v_add_f32_e32 v202, v202, v71
	v_add_f32_e32 v202, v202, v72
	v_mfma_f32_32x32x16_bf16 v[182:197], v[176:179], v[122:125], v[182:197]
	v_med3_f32 v80, v80, s4, v236
	v_exp_f32_e32 v80, v80
	v_med3_f32 v81, v81, s4, v236
	v_exp_f32_e32 v81, v81
	v_add_f32_e32 v202, v202, v73
	s_setprio 1
	ds_read_b128 v[162:165], v200 offset:24576
	ds_read_b128 v[166:169], v200 offset:28672
	ds_read_b128 v[170:173], v200 offset:32768
	ds_read_b128 v[176:179], v200 offset:36864
	v_cvt_pk_bf16_f32 v66, v66, v67
	v_cvt_pk_bf16_f32 v67, v68, v69
	v_cvt_pk_bf16_f32 v68, v70, v71
	v_cvt_pk_bf16_f32 v69, v72, v73
	v_add_f32_e32 v202, v202, v74
	v_add_f32_e32 v202, v202, v75
	s_waitcnt lgkmcnt(8)
	v_mfma_f32_32x32x16_bf16 v[50:65], v[66:69], v[130:133], v[50:65]
	v_med3_f32 v182, v182, s4, v236
	v_exp_f32_e32 v182, v182
	v_med3_f32 v183, v183, s4, v236
	v_exp_f32_e32 v183, v183
	v_add_f32_e32 v202, v202, v76
	v_add_f32_e32 v202, v202, v77
	v_mfma_f32_32x32x16_bf16 v[34:49], v[66:69], v[134:137], v[34:49]
	v_med3_f32 v184, v184, s4, v236
	v_exp_f32_e32 v184, v184
	v_med3_f32 v185, v185, s4, v236
	v_exp_f32_e32 v185, v185
	v_add_f32_e32 v202, v202, v78
	v_add_f32_e32 v202, v202, v79
	v_mfma_f32_32x32x16_bf16 v[18:33], v[66:69], v[138:141], v[18:33]
	v_med3_f32 v186, v186, s4, v236
	v_exp_f32_e32 v186, v186
	v_med3_f32 v187, v187, s4, v236
	v_exp_f32_e32 v187, v187
	v_add_f32_e32 v202, v202, v80
	v_add_f32_e32 v202, v202, v81
	v_mfma_f32_32x32x16_bf16 v[2:17], v[66:69], v[142:145], v[2:17]
	v_med3_f32 v188, v188, s4, v236
	v_exp_f32_e32 v188, v188
	v_med3_f32 v189, v189, s4, v236
	v_exp_f32_e32 v189, v189
	v_cvt_pk_bf16_f32 v70, v74, v75
	v_cvt_pk_bf16_f32 v71, v76, v77
	v_cvt_pk_bf16_f32 v72, v78, v79
	v_cvt_pk_bf16_f32 v73, v80, v81
	ds_read_b128 v[130:133], v201 offset:24576
	ds_read_b128 v[134:137], v201 offset:28672
	ds_read_b128 v[138:141], v201 offset:32768
	ds_read_b128 v[142:145], v201 offset:36864
	s_waitcnt lgkmcnt(8)
	v_mfma_f32_32x32x16_bf16 v[50:65], v[70:73], v[146:149], v[50:65]
	v_med3_f32 v190, v190, s4, v236
	v_exp_f32_e32 v190, v190
	v_med3_f32 v191, v191, s4, v236
	v_exp_f32_e32 v191, v191
	v_add_f32_e32 v203, v182, v183
	v_add_f32_e32 v203, v203, v184
	v_mfma_f32_32x32x16_bf16 v[34:49], v[70:73], v[150:153], v[34:49]
	v_med3_f32 v192, v192, s4, v236
	v_exp_f32_e32 v192, v192
	v_med3_f32 v193, v193, s4, v236
	v_exp_f32_e32 v193, v193
	v_add_f32_e32 v203, v203, v185
	v_add_f32_e32 v203, v203, v186
	v_mfma_f32_32x32x16_bf16 v[18:33], v[70:73], v[154:157], v[18:33]
	v_med3_f32 v194, v194, s4, v236
	v_exp_f32_e32 v194, v194
	v_med3_f32 v195, v195, s4, v236
	v_exp_f32_e32 v195, v195
	v_add_f32_e32 v203, v203, v187
	v_mfma_f32_32x32x16_bf16 v[2:17], v[70:73], v[158:161], v[2:17]
	v_med3_f32 v196, v196, s4, v236
	v_exp_f32_e32 v196, v196
	v_med3_f32 v197, v197, s4, v236
	v_exp_f32_e32 v197, v197
	v_add_f32_e32 v203, v203, v188
	v_cvt_pk_bf16_f32 v182, v182, v183
	v_cvt_pk_bf16_f32 v183, v184, v185
	v_cvt_pk_bf16_f32 v184, v186, v187
	v_cvt_pk_bf16_f32 v185, v188, v189
	v_add_f32_e32 v203, v203, v189
	s_setprio 0
	s_waitcnt lgkmcnt(4)
	v_mfma_f32_32x32x16_bf16 v[50:65], v[182:185], v[162:165], v[50:65]
	v_mad_u64_u32 v[204:205], s[10:11], s86, v228, v[174:175]
	s_mul_i32 s10, s7, 0xa000
	s_add_i32 s10, s0, s10
	s_mov_b32 m0, s10
	v_lshl_add_u64 v[206:207], v[204:205], 0, s[94:95]
	global_load_lds_dwordx4 v[204:205], off
	v_add_f32_e32 v203, v203, v190
	v_add_f32_e32 v203, v203, v191
	v_add_f32_e32 v203, v203, v192
	v_mfma_f32_32x32x16_bf16 v[34:49], v[182:185], v[166:169], v[34:49]
	s_add_i32 m0, s10, 0x2000
	v_lshl_add_u64 v[204:205], v[204:205], 0, s[96:97]
	global_load_lds_dwordx4 v[206:207], off
	v_add_f32_e32 v203, v203, v193
	v_add_f32_e32 v203, v203, v194
	v_add_f32_e32 v203, v203, v195
	v_mfma_f32_32x32x16_bf16 v[18:33], v[182:185], v[170:173], v[18:33]
	s_add_i32 m0, s10, 0x4000
	s_nop 0
	global_load_lds_dwordx4 v[204:205], off
	v_lshl_add_u64 v[204:205], s[86:87], 1, v[180:181]
	s_add_i32 m0, s10, 0x6000
	v_add_f32_e32 v203, v203, v196
	v_add_f32_e32 v203, v203, v197
	v_cvt_pk_bf16_f32 v186, v190, v191
	v_cvt_pk_bf16_f32 v187, v192, v193
	v_cvt_pk_bf16_f32 v188, v194, v195
	v_cvt_pk_bf16_f32 v189, v196, v197
	v_mfma_f32_32x32x16_bf16 v[2:17], v[182:185], v[176:179], v[2:17]
	global_load_lds_dwordx4 v[204:205], off
	v_lshl_add_u64 v[204:205], v[204:205], 0, s[92:93]
	s_add_i32 m0, s10, 0x8000
	v_add_f32_e32 v202, v202, v203
	v_add_f32_e32 v0, v0, v202
	s_waitcnt lgkmcnt(0)
	v_mfma_f32_32x32x16_bf16 v[50:65], v[186:189], v[130:133], v[50:65]
	global_load_lds_dwordx4 v[204:205], off
	v_mfma_f32_32x32x16_bf16 v[34:49], v[186:189], v[134:137], v[34:49]
	v_mfma_f32_32x32x16_bf16 v[18:33], v[186:189], v[138:141], v[18:33]
	v_mfma_f32_32x32x16_bf16 v[2:17], v[186:189], v[142:145], v[2:17]
	s_waitcnt vmcnt(5) lgkmcnt(0)
	s_branch .LBB0_573
